# v17 stack + dead-code elimination of the leftover bpermute index arithmetic in the attention softmax (30 VALU removed)
# speedup vs baseline: 1.0048x; 1.0009x over previous
; #define LAS __attribute__((address_space(3)))
; __device__ __forceinline__ void attn_unit(LAS unsigned char* lds, bf16_t* proj, const float* biasG, const float* sink, int s, int qb, int kh, int hp, bf16_t* dummy = nullptr) {
;     ...
;             if (st < wq || st > wq + 8) continue;
;             f32x4 sa[2][2];
; #pragma unroll
;             for (int kt = 0; kt < 2; ++kt) { sa[kt][0] = (f32x4){0.f, 0.f, 0.f, 0.f}; sa[kt][1] = (f32x4){0.f, 0.f, 0.f, 0.f}; }
; #pragma unroll
;             for (int ks = 0; ks < 4; ++ks)
; #pragma unroll
;                 for (int kt = 0; kt < 2; ++kt) {
;                     const bf16x8 kf = *(const LAS bf16x8*)(Ks + (si * 32 + kt * 16 + l16) * 272 + ks * 64 + kg * 16);
;                     sa[kt][0] = __builtin_amdgcn_mfma_f32_16x16x32_bf16(kf, qf[0][ks], sa[kt][0], 0, 0, 0);
;                     sa[kt][1] = __builtin_amdgcn_mfma_f32_16x16x32_bf16(kf, qf[1][ks], sa[kt][1], 0, 0, 0);
;                 }
;             bf16x8 pf[2];
; #pragma unroll
;             for (int qt = 0; qt < 2; ++qt) {
;                 const int qp = wq * 32 + qt * 16 + l16;
;                 float sv[8]; float mx = -1e30f;
; #pragma unroll
;                 for (int kt = 0; kt < 2; ++kt)
; #pragma unroll
;                     for (int r = 0; r < 4; ++r) {
;                         const int kp = (kbi - 1) * 128 + si * 32 + kt * 16 + kg * 4 + r;
;                         const int rel = kp - qp; const bool valid = (rel >= -128) && (rel <= 128);
;                         const int idx = min(max(rel + 128, 0), 256);
;                         const float v = valid ? (sa[kt][qt][r] * SC + bL[hl * 260 + idx]) : -1e30f;
;                         sv[kt * 4 + r] = v; mx = fmaxf(mx, v);
;                     }
;                 mx = fmaxf(mx, __shfl_xor(mx, 16)); mx = fmaxf(mx, __shfl_xor(mx, 32));
.LBB0_665:
	s_add_i32 s19, s30, -3
	v_cmp_ge_u32_e32 vcc, s19, v192
	v_cmp_le_u32_e64 s[4:5], s19, v195
	s_and_b64 s[4:5], vcc, s[4:5]
	s_and_saveexec_b64 s[74:75], s[4:5]
	s_cbranch_execz .LBB0_699
	v_add_u32_e32 v251, 0x11700, v200
	v_add_u32_e32 v251, v251, v196
	v_add_u32_e32 v252, 0x11700, v201
	v_add_u32_e32 v252, v252, v196
	ds_read_b32 v235, v252 offset:256
	ds_read_b32 v236, v252 offset:260
	ds_read_b32 v237, v252 offset:264
	ds_read_b32 v238, v252 offset:268
	ds_read_b32 v239, v252 offset:320
	ds_read_b32 v240, v252 offset:324
	ds_read_b32 v241, v252 offset:328
	ds_read_b32 v242, v252 offset:332
	ds_read_b32 v243, v251 offset:192
	ds_read_b32 v244, v251 offset:196
	ds_read_b32 v245, v251 offset:200
	ds_read_b32 v246, v251 offset:204
	ds_read_b32 v247, v252 offset:256
	ds_read_b32 v248, v252 offset:260
	ds_read_b32 v249, v252 offset:264
	ds_read_b32 v250, v252 offset:268
	ds_read_b128 v[140:143], v213
	ds_read_b128 v[132:135], v213 offset:4352
	ds_read_b128 v[226:229], v213 offset:64
	ds_read_b128 v[230:233], v213 offset:4416
	v_add_u32_e32 v1, 0xffffff8d, v199
	v_cmp_gt_u32_e32 vcc, s53, v1
	v_add3_u32 v2, v201, v196, s31
	s_waitcnt lgkmcnt(3)
	v_mfma_f32_16x16x32_bf16 v[144:147], v[140:143], v[4:7], 0
	v_mfma_f32_16x16x32_bf16 v[140:143], v[140:143], v[20:23], 0
	s_waitcnt lgkmcnt(2)
	v_mfma_f32_16x16x32_bf16 v[136:139], v[132:135], v[20:23], 0
	v_mfma_f32_16x16x32_bf16 v[132:135], v[132:135], v[4:7], 0
	s_waitcnt lgkmcnt(1)
	v_mfma_f32_16x16x32_bf16 v[144:147], v[226:229], v[8:11], v[144:147]
	v_mfma_f32_16x16x32_bf16 v[140:143], v[226:229], v[24:27], v[140:143]
	ds_read_b128 v[226:229], v213 offset:128
	s_waitcnt lgkmcnt(1)
	v_mfma_f32_16x16x32_bf16 v[132:135], v[230:233], v[8:11], v[132:135]
	v_mfma_f32_16x16x32_bf16 v[136:139], v[230:233], v[24:27], v[136:139]
	ds_read_b128 v[230:233], v213 offset:4480
	s_waitcnt lgkmcnt(1)
	v_mfma_f32_16x16x32_bf16 v[144:147], v[226:229], v[12:15], v[144:147]
	v_mfma_f32_16x16x32_bf16 v[140:143], v[226:229], v[28:31], v[140:143]
	ds_read_b128 v[226:229], v213 offset:192
	s_waitcnt lgkmcnt(1)
	v_mfma_f32_16x16x32_bf16 v[132:135], v[230:233], v[12:15], v[132:135]
	v_mfma_f32_16x16x32_bf16 v[136:139], v[230:233], v[28:31], v[136:139]
	ds_read_b128 v[230:233], v213 offset:4544
	s_waitcnt lgkmcnt(1)
	v_mfma_f32_16x16x32_bf16 v[144:147], v[226:229], v[16:19], v[144:147]
	v_mfma_f32_16x16x32_bf16 v[140:143], v[226:229], v[32:35], v[140:143]
	s_waitcnt lgkmcnt(0)
	v_mfma_f32_16x16x32_bf16 v[132:135], v[230:233], v[16:19], v[132:135]
	v_mfma_f32_16x16x32_bf16 v[136:139], v[230:233], v[32:35], v[136:139]
	s_nop 2
	v_mov_b32_e32 v251, 0xf149f2ca
	s_waitcnt lgkmcnt(0)
	v_fmac_f32_e32 v235, 0x3e0293ee, v144
	v_cndmask_b32_e32 v229, v251, v235, vcc
	v_add_u32_e32 v1, 0xffffff8e, v199
	v_cmp_gt_u32_e64 s[4:5], s53, v1
	v_add3_u32 v225, v201, v196, s40
	v_fmac_f32_e32 v236, 0x3e0293ee, v145
	v_cndmask_b32_e64 v228, v251, v236, s[4:5]
	v_add_u32_e32 v1, 0xffffff8f, v199
	v_cmp_gt_u32_e64 s[6:7], s53, v1
	v_add3_u32 v226, v201, v196, s42
	v_fmac_f32_e32 v237, 0x3e0293ee, v146
	v_cndmask_b32_e64 v230, v251, v237, s[6:7]
	v_add_u32_e32 v1, 0xffffff90, v199
	v_cmp_gt_u32_e64 s[8:9], s53, v1
	v_add3_u32 v227, v201, v196, s96
	v_fmac_f32_e32 v238, 0x3e0293ee, v147
	v_cndmask_b32_e64 v145, v251, v238, s[8:9]
	v_add_u32_e32 v1, 0xffffff9d, v199
	v_cmp_gt_u32_e64 s[10:11], s53, v1
	v_fmac_f32_e32 v239, 0x3e0293ee, v132
	s_nop 0
	v_cndmask_b32_e64 v231, v251, v239, s[10:11]
	v_add_u32_e32 v1, 0xffffff9e, v199
	v_cmp_gt_u32_e64 s[10:11], s53, v1
	v_fmac_f32_e32 v240, 0x3e0293ee, v133
	s_nop 0
	v_cndmask_b32_e64 v232, v251, v240, s[10:11]
	v_add_u32_e32 v1, 0xffffff9f, v199
	v_cmp_gt_u32_e64 s[10:11], s53, v1
	v_fmac_f32_e32 v241, 0x3e0293ee, v134
	s_nop 0
	v_cndmask_b32_e64 v133, v251, v241, s[10:11]
	v_add_u32_e32 v1, 0xffffffa0, v199
	v_cmp_gt_u32_e64 s[10:11], s53, v1
	v_fmac_f32_e32 v242, 0x3e0293ee, v135
	s_nop 0
	v_cndmask_b32_e64 v132, v251, v242, s[10:11]
	v_mov_b32_e32 v144, 0xf149f2ca
	v_max3_f32 v1, v229, v144, v228
	v_max3_f32 v1, v1, v230, v145
	v_max3_f32 v1, v1, v231, v232
	v_max3_f32 v1, v1, v133, v132
	v_mov_b32_e32 v253, v1
	v_mov_b32_e32 v135, v1
	s_nop 1
	v_permlane16_swap_b32_e32 v253, v135
	v_max_f32_e32 v135, v135, v253
	s_waitcnt lgkmcnt(0)
	v_max_f32_e32 v134, v135, v135
	v_max_f32_e32 v1, v1, v134
	v_mov_b32_e32 v253, v1
	v_mov_b32_e32 v134, v1
	s_nop 1
	v_permlane32_swap_b32_e32 v253, v134
	v_max_f32_e32 v134, v134, v253
	s_waitcnt lgkmcnt(0)
; #define LAS __attribute__((address_space(3)))
; __device__ __forceinline__ unsigned cvt_pk_bf16(float lo, float hi) { unsigned r; asm volatile("v_cvt_pk_bf16_f32 %0, %1, %2" : "=v"(r) : "v"(lo), "v"(hi)); return r; }
; __device__ __forceinline__ void attn_unit(LAS unsigned char* lds, bf16_t* proj, const float* biasG, const float* sink, int s, int qb, int kh, int hp, bf16_t* dummy = nullptr) {
;     ...
;                     for (int r = 0; r < 4; ++r) {
;                         const int kp = (kbi - 1) * 128 + si * 32 + kt * 16 + kg * 4 + r;
;                         const int rel = kp - qp; const bool valid = (rel >= -128) && (rel <= 128);
;                         const int idx = min(max(rel + 128, 0), 256);
;                         const float v = valid ? (sa[kt][qt][r] * SC + bL[hl * 260 + idx]) : -1e30f;
;                         sv[kt * 4 + r] = v; mx = fmaxf(mx, v);
;                     }
;                 mx = fmaxf(mx, __shfl_xor(mx, 16)); mx = fmaxf(mx, __shfl_xor(mx, 32));
;                 const float mnew = fmaxf(m2[qt], mx), alpha = __builtin_amdgcn_exp2f(m2[qt] - mnew); m2[qt] = mnew;
;                 float ps = 0.f; float pv[8];
; #pragma unroll
;                 for (int i = 0; i < 8; ++i) { pv[i] = __builtin_amdgcn_exp2f(sv[i] - mnew); ps += pv[i]; }
;                 lsum[qt] = lsum[qt] * alpha + ps;
; #pragma unroll
;                 for (int dt = 0; dt < 8; ++dt) o[dt][qt] = o[dt][qt] * alpha;
;                 u32x4 pw; pw.x = cvt_pk_bf16(pv[0], pv[1]); pw.y = cvt_pk_bf16(pv[2], pv[3]); pw.z = cvt_pk_bf16(pv[4], pv[5]); pw.w = cvt_pk_bf16(pv[6], pv[7]);
;                 pf[qt] = __builtin_bit_cast(bf16x8, pw);
;             }
; #pragma unroll
;             for (int dt = 0; dt < 8; ++dt) {
;                 const LAS unsigned char* vr = Vt + (dt * 16 + l16) * 288 + (si * 32 + kg * 4) * 2;
;                 const u32x2 lo = *(const LAS u32x2*)(vr), hi = *(const LAS u32x2*)(vr + 32);
	v_max3_f32 v1, v224, v1, v134
	v_sub_f32_e32 v134, v229, v1
	v_exp_f32_e32 v147, v134
	v_sub_f32_e32 v134, v228, v1
	v_exp_f32_e32 v228, v134
	v_sub_f32_e32 v134, v230, v1
	v_exp_f32_e32 v229, v134
	v_sub_f32_e32 v134, v145, v1
	v_exp_f32_e32 v230, v134
	v_sub_f32_e32 v134, v231, v1
	v_exp_f32_e32 v231, v134
	v_sub_f32_e32 v134, v232, v1
	v_sub_f32_e32 v133, v133, v1
	v_sub_f32_e32 v132, v132, v1
	v_exp_f32_e32 v232, v134
	v_exp_f32_e32 v233, v133
	v_exp_f32_e32 v234, v132
	v_add_u32_e32 v145, 0xffffff7d, v199
	v_cmp_gt_u32_e64 s[10:11], s53, v145
	v_cvt_pk_bf16_f32 v132, v147, v228
	v_cvt_pk_bf16_f32 v133, v229, v230
	v_cvt_pk_bf16_f32 v134, v231, v232
	v_cvt_pk_bf16_f32 v135, v233, v234
	v_fmac_f32_e32 v243, 0x3e0293ee, v140
	v_cndmask_b32_e64 v145, v251, v243, s[10:11]
	v_add_u32_e32 v140, 0xffffff7e, v199
	v_cmp_gt_u32_e64 s[10:11], s53, v140
	v_fmac_f32_e32 v244, 0x3e0293ee, v141
	s_nop 0
	v_cndmask_b32_e64 v144, v144, v244, s[10:11]
	v_add_u32_e32 v140, 0xffffff7f, v199
	v_cmp_gt_u32_e64 s[10:11], s53, v140
	v_fmac_f32_e32 v245, 0x3e0293ee, v142
	s_nop 0
	v_cndmask_b32_e64 v141, v251, v245, s[10:11]
	v_add_u32_e32 v142, 0xffffff80, v199
	v_cmp_gt_u32_e64 s[10:11], s53, v142
	v_fmac_f32_e32 v246, 0x3e0293ee, v143
	s_nop 0
	v_cndmask_b32_e64 v140, v251, v246, s[10:11]
	v_fmac_f32_e32 v247, 0x3e0293ee, v136
	v_cndmask_b32_e32 v143, v251, v247, vcc
	v_fmac_f32_e32 v248, 0x3e0293ee, v137
	v_cndmask_b32_e64 v142, v251, v248, s[4:5]
	v_fmac_f32_e32 v249, 0x3e0293ee, v138
	v_cndmask_b32_e64 v137, v251, v249, s[6:7]
	v_fmac_f32_e32 v250, 0x3e0293ee, v139
	v_cndmask_b32_e64 v136, v251, v250, s[8:9]
	v_max3_f32 v2, v145, s89, v144
	v_max3_f32 v2, v2, v141, v140
	v_max3_f32 v139, v2, v143, v142
	v_add_f32_e32 v2, 0, v147
	v_add_f32_e32 v2, v228, v2
	v_add_f32_e32 v2, v229, v2
	v_sub_f32_e32 v138, v224, v1
	v_add_f32_e32 v2, v230, v2
	v_add_f32_e32 v2, v231, v2
	v_exp_f32_e32 v138, v138
	v_add_f32_e32 v2, v232, v2
	v_add_f32_e32 v2, v233, v2
	v_add_f32_e32 v2, v234, v2
	v_fmac_f32_e32 v2, v223, v138
	v_pk_mul_f32 v[98:99], v[98:99], v[138:139] op_sel_hi:[1,0]
	v_pk_mul_f32 v[96:97], v[96:97], v[138:139] op_sel_hi:[1,0]
	v_pk_mul_f32 v[106:107], v[106:107], v[138:139] op_sel_hi:[1,0]
	v_pk_mul_f32 v[104:105], v[104:105], v[138:139] op_sel_hi:[1,0]
	v_pk_mul_f32 v[110:111], v[110:111], v[138:139] op_sel_hi:[1,0]
	v_pk_mul_f32 v[108:109], v[108:109], v[138:139] op_sel_hi:[1,0]
	v_pk_mul_f32 v[114:115], v[114:115], v[138:139] op_sel_hi:[1,0]
	v_pk_mul_f32 v[112:113], v[112:113], v[138:139] op_sel_hi:[1,0]
	v_pk_mul_f32 v[118:119], v[118:119], v[138:139] op_sel_hi:[1,0]
	v_pk_mul_f32 v[116:117], v[116:117], v[138:139] op_sel_hi:[1,0]
	v_pk_mul_f32 v[122:123], v[122:123], v[138:139] op_sel_hi:[1,0]
	v_pk_mul_f32 v[120:121], v[120:121], v[138:139] op_sel_hi:[1,0]
	v_pk_mul_f32 v[126:127], v[126:127], v[138:139] op_sel_hi:[1,0]
	v_pk_mul_f32 v[124:125], v[124:125], v[138:139] op_sel_hi:[1,0]
	v_pk_mul_f32 v[130:131], v[130:131], v[138:139] op_sel_hi:[1,0]
	v_pk_mul_f32 v[128:129], v[128:129], v[138:139] op_sel_hi:[1,0]
	v_max3_f32 v138, v139, v137, v136
	v_mov_b32_e32 v253, v138
	v_mov_b32_e32 v139, v138
	s_nop 1
	v_permlane16_swap_b32_e32 v253, v139
	v_max_f32_e32 v139, v139, v253
	v_mov_b32_e32 v223, v2
	v_mov_b32_e32 v224, v1
	s_waitcnt lgkmcnt(0)
	v_max_f32_e32 v139, v139, v139
	v_max_f32_e32 v138, v138, v139
	v_mov_b32_e32 v253, v138
	v_mov_b32_e32 v3, v138
	s_nop 1
	v_permlane32_swap_b32_e32 v253, v3
	v_max_f32_e32 v3, v3, v253
	s_waitcnt lgkmcnt(0)
	v_max3_f32 v3, v222, v138, v3
	v_sub_f32_e32 v139, v145, v3
	v_exp_f32_e32 v139, v139
	v_sub_f32_e32 v144, v144, v3
	v_exp_f32_e32 v144, v144
	v_sub_f32_e32 v141, v141, v3
	v_exp_f32_e32 v141, v141
	v_sub_f32_e32 v140, v140, v3
	v_exp_f32_e32 v146, v140
	v_add_f32_e32 v145, 0, v139
	v_sub_f32_e32 v143, v143, v3
	v_add_f32_e32 v145, v144, v145
	v_exp_f32_e32 v143, v143
	v_sub_f32_e32 v142, v142, v3
	v_add_f32_e32 v145, v141, v145
	v_exp_f32_e32 v142, v142
	v_sub_f32_e32 v137, v137, v3
	v_add_f32_e32 v140, v146, v145
	v_exp_f32_e32 v145, v137
	v_sub_f32_e32 v136, v136, v3
	v_sub_f32_e32 v138, v222, v3
	v_exp_f32_e32 v147, v136
	v_add_f32_e32 v140, v143, v140
	v_exp_f32_e32 v136, v138
	v_add_f32_e32 v140, v142, v140
	v_add_f32_e32 v137, v145, v140
	v_add_f32_e32 v140, v147, v137
	v_fmac_f32_e32 v140, v221, v136
	v_pk_mul_f32 v[70:71], v[70:71], v[136:137] op_sel_hi:[1,0]
	v_pk_mul_f32 v[68:69], v[68:69], v[136:137] op_sel_hi:[1,0]
	v_pk_mul_f32 v[74:75], v[74:75], v[136:137] op_sel_hi:[1,0]
	v_pk_mul_f32 v[72:73], v[72:73], v[136:137] op_sel_hi:[1,0]
	v_pk_mul_f32 v[78:79], v[78:79], v[136:137] op_sel_hi:[1,0]
	v_pk_mul_f32 v[76:77], v[76:77], v[136:137] op_sel_hi:[1,0]
	v_pk_mul_f32 v[82:83], v[82:83], v[136:137] op_sel_hi:[1,0]
	v_pk_mul_f32 v[80:81], v[80:81], v[136:137] op_sel_hi:[1,0]
	v_pk_mul_f32 v[86:87], v[86:87], v[136:137] op_sel_hi:[1,0]
	v_pk_mul_f32 v[84:85], v[84:85], v[136:137] op_sel_hi:[1,0]
	v_pk_mul_f32 v[90:91], v[90:91], v[136:137] op_sel_hi:[1,0]
	v_pk_mul_f32 v[88:89], v[88:89], v[136:137] op_sel_hi:[1,0]
	v_pk_mul_f32 v[94:95], v[94:95], v[136:137] op_sel_hi:[1,0]
	v_pk_mul_f32 v[92:93], v[92:93], v[136:137] op_sel_hi:[1,0]
	v_pk_mul_f32 v[102:103], v[102:103], v[136:137] op_sel_hi:[1,0]
	v_pk_mul_f32 v[100:101], v[100:101], v[136:137] op_sel_hi:[1,0]
	v_cvt_pk_bf16_f32 v136, v139, v144
	v_cvt_pk_bf16_f32 v137, v141, v146
	v_add_u32_e32 v141, v197, v198
	v_cvt_pk_bf16_f32 v138, v143, v142
	v_add_u32_e32 v142, 0x8800, v141
	v_cvt_pk_bf16_f32 v139, v145, v147
	ds_read2_b64 v[236:239], v142 offset1:4
	v_mov_b32_e32 v221, v140
	v_add_u32_e32 v252, 0x9800, v141
	ds_read2_b64 v[240:243], v252 offset0:64 offset1:68
	v_add_u32_e32 v252, 0xa800, v141
	ds_read2_b64 v[244:247], v252 offset0:128 offset1:132
	v_add_u32_e32 v252, 0xb800, v141
	ds_read2_b64 v[248:251], v252 offset0:192 offset1:196
	s_waitcnt lgkmcnt(3)
; __device__ __forceinline__ void attn_unit(LAS unsigned char* lds, bf16_t* proj, const float* biasG, const float* sink, int s, int qb, int kh, int hp, bf16_t* dummy = nullptr) {
;     ...
;             if (st < wq || st > wq + 8) continue;
;             f32x4 sa[2][2];
; #pragma unroll
;             for (int kt = 0; kt < 2; ++kt) { sa[kt][0] = (f32x4){0.f, 0.f, 0.f, 0.f}; sa[kt][1] = (f32x4){0.f, 0.f, 0.f, 0.f}; }
; #pragma unroll
;             for (int ks = 0; ks < 4; ++ks)
; #pragma unroll
;                 for (int kt = 0; kt < 2; ++kt) {
;                     const bf16x8 kf = *(const LAS bf16x8*)(Ks + (si * 32 + kt * 16 + l16) * 272 + ks * 64 + kg * 16);
;                     sa[kt][0] = __builtin_amdgcn_mfma_f32_16x16x32_bf16(kf, qf[0][ks], sa[kt][0], 0, 0, 0);
;                     sa[kt][1] = __builtin_amdgcn_mfma_f32_16x16x32_bf16(kf, qf[1][ks], sa[kt][1], 0, 0, 0);
;                 }
;             bf16x8 pf[2];
; #pragma unroll
;             for (int qt = 0; qt < 2; ++qt) {
;                 const int qp = wq * 32 + qt * 16 + l16;
;                 float sv[8]; float mx = -1e30f;
; #pragma unroll
;                 for (int kt = 0; kt < 2; ++kt)
; #pragma unroll
;                     for (int r = 0; r < 4; ++r) {
;                         const int kp = (kbi - 1) * 128 + si * 32 + kt * 16 + kg * 4 + r;
;                         const int rel = kp - qp; const bool valid = (rel >= -128) && (rel <= 128);
;                         const int idx = min(max(rel + 128, 0), 256);
;                         const float v = valid ? (sa[kt][qt][r] * SC + bL[hl * 260 + idx]) : -1e30f;
;                         sv[kt * 4 + r] = v; mx = fmaxf(mx, v);
;                     }
;                 mx = fmaxf(mx, __shfl_xor(mx, 16)); mx = fmaxf(mx, __shfl_xor(mx, 32));
;     ...
;             for (int dt = 0; dt < 8; ++dt) {
;                 const LAS unsigned char* vr = Vt + (dt * 16 + l16) * 288 + (si * 32 + kg * 4) * 2;
;                 const u32x2 lo = *(const LAS u32x2*)(vr), hi = *(const LAS u32x2*)(vr + 32);
;                 u32x4 vw; vw.x = lo.x; vw.y = lo.y; vw.z = hi.x; vw.w = hi.y;
;                 const bf16x8 vf = __builtin_bit_cast(bf16x8, vw);
;                 o[dt][0] = __builtin_amdgcn_mfma_f32_16x16x32_bf16(vf, pf[0], o[dt][0], 0, 0, 0);
;                 o[dt][1] = __builtin_amdgcn_mfma_f32_16x16x32_bf16(vf, pf[1], o[dt][1], 0, 0, 0);
;             }
	v_mfma_f32_16x16x32_bf16 v[96:99], v[236:239], v[132:135], v[96:99]
	v_mov_b32_e32 v222, v3
	v_mfma_f32_16x16x32_bf16 v[68:71], v[236:239], v[136:139], v[68:71]
	v_add_u32_e32 v252, 0xd000, v141
	ds_read2_b64 v[236:239], v252 offset1:4
	s_waitcnt lgkmcnt(3)
	v_mfma_f32_16x16x32_bf16 v[104:107], v[240:243], v[132:135], v[104:107]
	v_mfma_f32_16x16x32_bf16 v[72:75], v[240:243], v[136:139], v[72:75]
	v_add_u32_e32 v252, 0xe000, v141
	ds_read2_b64 v[240:243], v252 offset0:64 offset1:68
	v_add_u32_e32 v141, 0xf000, v141
	s_waitcnt lgkmcnt(3)
	v_mfma_f32_16x16x32_bf16 v[108:111], v[244:247], v[132:135], v[108:111]
	v_mfma_f32_16x16x32_bf16 v[76:79], v[244:247], v[136:139], v[76:79]
	ds_read2_b64 v[244:247], v141 offset0:128 offset1:132
	s_waitcnt lgkmcnt(3)
	v_mfma_f32_16x16x32_bf16 v[112:115], v[248:251], v[132:135], v[112:115]
	v_mfma_f32_16x16x32_bf16 v[80:83], v[248:251], v[136:139], v[80:83]
	ds_read2_b64 v[248:251], v214 offset0:192 offset1:196
	s_waitcnt lgkmcnt(3)
	v_mfma_f32_16x16x32_bf16 v[116:119], v[236:239], v[132:135], v[116:119]
	v_mfma_f32_16x16x32_bf16 v[84:87], v[236:239], v[136:139], v[84:87]
	s_waitcnt lgkmcnt(2)
	v_mfma_f32_16x16x32_bf16 v[120:123], v[240:243], v[132:135], v[120:123]
	v_mfma_f32_16x16x32_bf16 v[88:91], v[240:243], v[136:139], v[88:91]
	s_waitcnt lgkmcnt(1)
	v_mfma_f32_16x16x32_bf16 v[124:127], v[244:247], v[132:135], v[124:127]
	v_mfma_f32_16x16x32_bf16 v[92:95], v[244:247], v[136:139], v[92:95]
	s_waitcnt lgkmcnt(0)
	v_mfma_f32_16x16x32_bf16 v[128:131], v[248:251], v[132:135], v[128:131]
	v_mfma_f32_16x16x32_bf16 v[100:103], v[248:251], v[136:139], v[100:103]
.LBB0_699:
	s_or_b64 exec, exec, s[74:75]
	s_add_i32 s4, s30, -2
	v_cmp_ge_u32_e32 vcc, s4, v192
	v_cmp_lt_u32_e64 s[4:5], s19, v195
	s_and_b64 s[4:5], vcc, s[4:5]
	s_and_saveexec_b64 s[74:75], s[4:5]
	s_cbranch_execz .LBB0_733
	v_add_u32_e32 v251, 0x11700, v201
	v_add_u32_e32 v251, v251, v196
	ds_read_b32 v235, v251 offset:384
	ds_read_b32 v236, v251 offset:388
	ds_read_b32 v237, v251 offset:392
	ds_read_b32 v238, v251 offset:396
	ds_read_b32 v239, v251 offset:448
	ds_read_b32 v240, v251 offset:452
	ds_read_b32 v241, v251 offset:456
	ds_read_b32 v242, v251 offset:460
	ds_read_b32 v243, v251 offset:320
	ds_read_b32 v244, v251 offset:324
	ds_read_b32 v245, v251 offset:328
	ds_read_b32 v246, v251 offset:332
	ds_read_b32 v247, v251 offset:384
	ds_read_b32 v248, v251 offset:388
	ds_read_b32 v249, v251 offset:392
	ds_read_b32 v250, v251 offset:396
	ds_read_b128 v[140:143], v210
	ds_read_b128 v[132:135], v213 offset:13056
	ds_read_b128 v[226:229], v210 offset:64
	ds_read_b128 v[230:233], v213 offset:13120
	v_add_u32_e32 v1, 0xffffffad, v199
	v_cmp_gt_u32_e32 vcc, s53, v1
	v_add3_u32 v2, v201, v196, s88
	s_waitcnt lgkmcnt(3)
	v_mfma_f32_16x16x32_bf16 v[144:147], v[140:143], v[4:7], 0
	v_mfma_f32_16x16x32_bf16 v[140:143], v[140:143], v[20:23], 0
	s_waitcnt lgkmcnt(2)
	v_mfma_f32_16x16x32_bf16 v[136:139], v[132:135], v[20:23], 0
	v_mfma_f32_16x16x32_bf16 v[132:135], v[132:135], v[4:7], 0
	s_waitcnt lgkmcnt(1)
	v_mfma_f32_16x16x32_bf16 v[144:147], v[226:229], v[8:11], v[144:147]
	v_mfma_f32_16x16x32_bf16 v[140:143], v[226:229], v[24:27], v[140:143]
	ds_read_b128 v[226:229], v210 offset:128
	s_waitcnt lgkmcnt(1)
	v_mfma_f32_16x16x32_bf16 v[132:135], v[230:233], v[8:11], v[132:135]
	v_mfma_f32_16x16x32_bf16 v[136:139], v[230:233], v[24:27], v[136:139]
	ds_read_b128 v[230:233], v213 offset:13184
	s_waitcnt lgkmcnt(1)
	v_mfma_f32_16x16x32_bf16 v[144:147], v[226:229], v[12:15], v[144:147]
	v_mfma_f32_16x16x32_bf16 v[140:143], v[226:229], v[28:31], v[140:143]
	ds_read_b128 v[226:229], v210 offset:192
	s_waitcnt lgkmcnt(1)
	v_mfma_f32_16x16x32_bf16 v[132:135], v[230:233], v[12:15], v[132:135]
	v_mfma_f32_16x16x32_bf16 v[136:139], v[230:233], v[28:31], v[136:139]
	ds_read_b128 v[230:233], v213 offset:13248
	s_waitcnt lgkmcnt(1)
	v_mfma_f32_16x16x32_bf16 v[144:147], v[226:229], v[16:19], v[144:147]
	v_mfma_f32_16x16x32_bf16 v[140:143], v[226:229], v[32:35], v[140:143]
	s_waitcnt lgkmcnt(0)
	v_mfma_f32_16x16x32_bf16 v[132:135], v[230:233], v[16:19], v[132:135]
	v_mfma_f32_16x16x32_bf16 v[136:139], v[230:233], v[32:35], v[136:139]
	s_nop 2
	v_mov_b32_e32 v251, 0xf149f2ca
	s_waitcnt lgkmcnt(0)
	v_fmac_f32_e32 v235, 0x3e0293ee, v144
	v_cndmask_b32_e32 v229, v251, v235, vcc
	v_add_u32_e32 v1, 0xffffffae, v199
	v_cmp_gt_u32_e64 s[4:5], s53, v1
	v_add3_u32 v225, v201, v196, s55
	v_fmac_f32_e32 v236, 0x3e0293ee, v145
	v_cndmask_b32_e64 v228, v251, v236, s[4:5]
	v_add_u32_e32 v1, 0xffffffaf, v199
	v_cmp_gt_u32_e64 s[6:7], s53, v1
	v_add3_u32 v226, v201, v196, s59
	v_fmac_f32_e32 v237, 0x3e0293ee, v146
	v_cndmask_b32_e64 v230, v251, v237, s[6:7]
	v_add_u32_e32 v1, 0xffffffb0, v199
	v_cmp_gt_u32_e64 s[8:9], s53, v1
	v_add3_u32 v227, v201, v196, s43
	v_fmac_f32_e32 v238, 0x3e0293ee, v147
	v_cndmask_b32_e64 v145, v251, v238, s[8:9]
	v_add_u32_e32 v1, 0xffffffbd, v199
	v_cmp_gt_u32_e64 s[10:11], s53, v1
	v_fmac_f32_e32 v239, 0x3e0293ee, v132
	s_nop 0
	v_cndmask_b32_e64 v231, v251, v239, s[10:11]
	v_add_u32_e32 v1, 0xffffffbe, v199
	v_cmp_gt_u32_e64 s[10:11], s53, v1
	v_fmac_f32_e32 v240, 0x3e0293ee, v133
	s_nop 0
	v_cndmask_b32_e64 v232, v251, v240, s[10:11]
	v_add_u32_e32 v1, 0xffffffbf, v199
	v_cmp_gt_u32_e64 s[10:11], s53, v1
	v_fmac_f32_e32 v241, 0x3e0293ee, v134
	s_nop 0
	v_cndmask_b32_e64 v133, v251, v241, s[10:11]
	v_subrev_u32_e32 v1, 64, v199
	v_cmp_gt_u32_e64 s[10:11], s53, v1
	v_fmac_f32_e32 v242, 0x3e0293ee, v135
	s_nop 0
	v_cndmask_b32_e64 v132, v251, v242, s[10:11]
	v_mov_b32_e32 v144, 0xf149f2ca
	v_max3_f32 v1, v229, v144, v228
	v_max3_f32 v1, v1, v230, v145
	v_max3_f32 v1, v1, v231, v232
	v_max3_f32 v1, v1, v133, v132
	v_mov_b32_e32 v253, v1
	v_mov_b32_e32 v135, v1
	s_nop 1
	v_permlane16_swap_b32_e32 v253, v135
	v_max_f32_e32 v135, v135, v253
	s_waitcnt lgkmcnt(0)
; #define LAS __attribute__((address_space(3)))
; __device__ __forceinline__ unsigned cvt_pk_bf16(float lo, float hi) { unsigned r; asm volatile("v_cvt_pk_bf16_f32 %0, %1, %2" : "=v"(r) : "v"(lo), "v"(hi)); return r; }
; __device__ __forceinline__ void attn_unit(LAS unsigned char* lds, bf16_t* proj, const float* biasG, const float* sink, int s, int qb, int kh, int hp, bf16_t* dummy = nullptr) {
;     ...
;                 float sv[8]; float mx = -1e30f;
; #pragma unroll
;                 for (int kt = 0; kt < 2; ++kt)
; #pragma unroll
;                     for (int r = 0; r < 4; ++r) {
;                         const int kp = (kbi - 1) * 128 + si * 32 + kt * 16 + kg * 4 + r;
;                         const int rel = kp - qp; const bool valid = (rel >= -128) && (rel <= 128);
;                         const int idx = min(max(rel + 128, 0), 256);
;                         const float v = valid ? (sa[kt][qt][r] * SC + bL[hl * 260 + idx]) : -1e30f;
;                         sv[kt * 4 + r] = v; mx = fmaxf(mx, v);
;                     }
;                 mx = fmaxf(mx, __shfl_xor(mx, 16)); mx = fmaxf(mx, __shfl_xor(mx, 32));
;                 const float mnew = fmaxf(m2[qt], mx), alpha = __builtin_amdgcn_exp2f(m2[qt] - mnew); m2[qt] = mnew;
;                 float ps = 0.f; float pv[8];
; #pragma unroll
;                 for (int i = 0; i < 8; ++i) { pv[i] = __builtin_amdgcn_exp2f(sv[i] - mnew); ps += pv[i]; }
;                 lsum[qt] = lsum[qt] * alpha + ps;
; #pragma unroll
;                 for (int dt = 0; dt < 8; ++dt) o[dt][qt] = o[dt][qt] * alpha;
;                 u32x4 pw; pw.x = cvt_pk_bf16(pv[0], pv[1]); pw.y = cvt_pk_bf16(pv[2], pv[3]); pw.z = cvt_pk_bf16(pv[4], pv[5]); pw.w = cvt_pk_bf16(pv[6], pv[7]);
;                 pf[qt] = __builtin_bit_cast(bf16x8, pw);
;             }
; #pragma unroll
;             for (int dt = 0; dt < 8; ++dt) {
;                 const LAS unsigned char* vr = Vt + (dt * 16 + l16) * 288 + (si * 32 + kg * 4) * 2;
;                 const u32x2 lo = *(const LAS u32x2*)(vr), hi = *(const LAS u32x2*)(vr + 32);
	v_max_f32_e32 v134, v135, v135
	v_max_f32_e32 v1, v1, v134
	v_mov_b32_e32 v253, v1
	v_mov_b32_e32 v134, v1
	s_nop 1
	v_permlane32_swap_b32_e32 v253, v134
	v_max_f32_e32 v134, v134, v253
	s_waitcnt lgkmcnt(0)
	v_max3_f32 v1, v224, v1, v134
	v_sub_f32_e32 v134, v229, v1
	v_exp_f32_e32 v147, v134
	v_sub_f32_e32 v134, v228, v1
	v_exp_f32_e32 v228, v134
	v_sub_f32_e32 v134, v230, v1
	v_exp_f32_e32 v229, v134
	v_sub_f32_e32 v134, v145, v1
	v_exp_f32_e32 v230, v134
	v_sub_f32_e32 v134, v231, v1
	v_exp_f32_e32 v231, v134
	v_sub_f32_e32 v134, v232, v1
	v_sub_f32_e32 v133, v133, v1
	v_sub_f32_e32 v132, v132, v1
	v_exp_f32_e32 v232, v134
	v_exp_f32_e32 v233, v133
	v_exp_f32_e32 v234, v132
	v_add_u32_e32 v145, 0xffffff9d, v199
	v_cmp_gt_u32_e64 s[10:11], s53, v145
	v_cvt_pk_bf16_f32 v132, v147, v228
	v_cvt_pk_bf16_f32 v133, v229, v230
	v_cvt_pk_bf16_f32 v134, v231, v232
	v_cvt_pk_bf16_f32 v135, v233, v234
	v_fmac_f32_e32 v243, 0x3e0293ee, v140
	v_cndmask_b32_e64 v145, v251, v243, s[10:11]
	v_add_u32_e32 v140, 0xffffff9e, v199
	v_cmp_gt_u32_e64 s[10:11], s53, v140
	v_fmac_f32_e32 v244, 0x3e0293ee, v141
	s_nop 0
	v_cndmask_b32_e64 v144, v144, v244, s[10:11]
	v_add_u32_e32 v140, 0xffffff9f, v199
	v_cmp_gt_u32_e64 s[10:11], s53, v140
	v_fmac_f32_e32 v245, 0x3e0293ee, v142
	s_nop 0
	v_cndmask_b32_e64 v141, v251, v245, s[10:11]
	v_add_u32_e32 v142, 0xffffffa0, v199
	v_cmp_gt_u32_e64 s[10:11], s53, v142
	v_fmac_f32_e32 v246, 0x3e0293ee, v143
	s_nop 0
	v_cndmask_b32_e64 v140, v251, v246, s[10:11]
	v_fmac_f32_e32 v247, 0x3e0293ee, v136
	v_cndmask_b32_e32 v143, v251, v247, vcc
	v_fmac_f32_e32 v248, 0x3e0293ee, v137
	v_cndmask_b32_e64 v142, v251, v248, s[4:5]
	v_fmac_f32_e32 v249, 0x3e0293ee, v138
	v_cndmask_b32_e64 v137, v251, v249, s[6:7]
	v_fmac_f32_e32 v250, 0x3e0293ee, v139
	v_cndmask_b32_e64 v136, v251, v250, s[8:9]
	v_max3_f32 v2, v145, s89, v144
	v_max3_f32 v2, v2, v141, v140
	v_max3_f32 v139, v2, v143, v142
	v_add_f32_e32 v2, 0, v147
	v_add_f32_e32 v2, v228, v2
	v_add_f32_e32 v2, v229, v2
	v_sub_f32_e32 v138, v224, v1
	v_add_f32_e32 v2, v230, v2
	v_add_f32_e32 v2, v231, v2
	v_exp_f32_e32 v138, v138
	v_add_f32_e32 v2, v232, v2
	v_add_f32_e32 v2, v233, v2
	v_add_f32_e32 v2, v234, v2
	v_fmac_f32_e32 v2, v223, v138
	v_pk_mul_f32 v[98:99], v[98:99], v[138:139] op_sel_hi:[1,0]
	v_pk_mul_f32 v[96:97], v[96:97], v[138:139] op_sel_hi:[1,0]
	v_pk_mul_f32 v[106:107], v[106:107], v[138:139] op_sel_hi:[1,0]
	v_pk_mul_f32 v[104:105], v[104:105], v[138:139] op_sel_hi:[1,0]
	v_pk_mul_f32 v[110:111], v[110:111], v[138:139] op_sel_hi:[1,0]
	v_pk_mul_f32 v[108:109], v[108:109], v[138:139] op_sel_hi:[1,0]
	v_pk_mul_f32 v[114:115], v[114:115], v[138:139] op_sel_hi:[1,0]
	v_pk_mul_f32 v[112:113], v[112:113], v[138:139] op_sel_hi:[1,0]
	v_pk_mul_f32 v[118:119], v[118:119], v[138:139] op_sel_hi:[1,0]
	v_pk_mul_f32 v[116:117], v[116:117], v[138:139] op_sel_hi:[1,0]
	v_pk_mul_f32 v[122:123], v[122:123], v[138:139] op_sel_hi:[1,0]
	v_pk_mul_f32 v[120:121], v[120:121], v[138:139] op_sel_hi:[1,0]
	v_pk_mul_f32 v[126:127], v[126:127], v[138:139] op_sel_hi:[1,0]
	v_pk_mul_f32 v[124:125], v[124:125], v[138:139] op_sel_hi:[1,0]
	v_pk_mul_f32 v[130:131], v[130:131], v[138:139] op_sel_hi:[1,0]
	v_pk_mul_f32 v[128:129], v[128:129], v[138:139] op_sel_hi:[1,0]
	v_max3_f32 v138, v139, v137, v136
	v_mov_b32_e32 v253, v138
	v_mov_b32_e32 v139, v138
	s_nop 1
	v_permlane16_swap_b32_e32 v253, v139
	v_max_f32_e32 v139, v139, v253
	v_mov_b32_e32 v223, v2
	v_mov_b32_e32 v224, v1
	s_waitcnt lgkmcnt(0)
	v_max_f32_e32 v139, v139, v139
	v_max_f32_e32 v138, v138, v139
	v_mov_b32_e32 v253, v138
	v_mov_b32_e32 v3, v138
	s_nop 1
	v_permlane32_swap_b32_e32 v253, v3
	v_max_f32_e32 v3, v3, v253
	s_waitcnt lgkmcnt(0)
	v_max3_f32 v3, v222, v138, v3
	v_sub_f32_e32 v139, v145, v3
	v_exp_f32_e32 v139, v139
	v_sub_f32_e32 v144, v144, v3
	v_exp_f32_e32 v144, v144
	v_sub_f32_e32 v141, v141, v3
	v_exp_f32_e32 v141, v141
	v_sub_f32_e32 v140, v140, v3
	v_exp_f32_e32 v146, v140
	v_add_f32_e32 v145, 0, v139
	v_sub_f32_e32 v143, v143, v3
	v_add_f32_e32 v145, v144, v145
	v_exp_f32_e32 v143, v143
	v_sub_f32_e32 v142, v142, v3
	v_add_f32_e32 v145, v141, v145
	v_exp_f32_e32 v142, v142
	v_sub_f32_e32 v137, v137, v3
	v_add_f32_e32 v140, v146, v145
	v_exp_f32_e32 v145, v137
	v_sub_f32_e32 v136, v136, v3
	v_sub_f32_e32 v138, v222, v3
	v_exp_f32_e32 v147, v136
	v_add_f32_e32 v140, v143, v140
	v_exp_f32_e32 v136, v138
	v_add_f32_e32 v140, v142, v140
	v_add_f32_e32 v137, v145, v140
	v_add_f32_e32 v140, v147, v137
	v_fmac_f32_e32 v140, v221, v136
	v_pk_mul_f32 v[70:71], v[70:71], v[136:137] op_sel_hi:[1,0]
	v_pk_mul_f32 v[68:69], v[68:69], v[136:137] op_sel_hi:[1,0]
	v_pk_mul_f32 v[74:75], v[74:75], v[136:137] op_sel_hi:[1,0]
	v_pk_mul_f32 v[72:73], v[72:73], v[136:137] op_sel_hi:[1,0]
	v_pk_mul_f32 v[78:79], v[78:79], v[136:137] op_sel_hi:[1,0]
	v_pk_mul_f32 v[76:77], v[76:77], v[136:137] op_sel_hi:[1,0]
	v_pk_mul_f32 v[82:83], v[82:83], v[136:137] op_sel_hi:[1,0]
	v_pk_mul_f32 v[80:81], v[80:81], v[136:137] op_sel_hi:[1,0]
	v_pk_mul_f32 v[86:87], v[86:87], v[136:137] op_sel_hi:[1,0]
	v_pk_mul_f32 v[84:85], v[84:85], v[136:137] op_sel_hi:[1,0]
	v_pk_mul_f32 v[90:91], v[90:91], v[136:137] op_sel_hi:[1,0]
	v_pk_mul_f32 v[88:89], v[88:89], v[136:137] op_sel_hi:[1,0]
	v_pk_mul_f32 v[94:95], v[94:95], v[136:137] op_sel_hi:[1,0]
	v_pk_mul_f32 v[92:93], v[92:93], v[136:137] op_sel_hi:[1,0]
	v_pk_mul_f32 v[102:103], v[102:103], v[136:137] op_sel_hi:[1,0]
	v_pk_mul_f32 v[100:101], v[100:101], v[136:137] op_sel_hi:[1,0]
	v_cvt_pk_bf16_f32 v136, v139, v144
	v_cvt_pk_bf16_f32 v137, v141, v146
	v_add_u32_e32 v141, v197, v198
	v_cvt_pk_bf16_f32 v138, v143, v142
	v_add_u32_e32 v142, 0x8800, v141
	v_cvt_pk_bf16_f32 v139, v145, v147
	ds_read2_b64 v[236:239], v142 offset0:8 offset1:12
	v_mov_b32_e32 v221, v140
	v_add_u32_e32 v252, 0x9800, v141
	ds_read2_b64 v[240:243], v252 offset0:72 offset1:76
	ds_read2_b64 v[244:247], v215 offset0:8 offset1:12
	v_add_u32_e32 v252, 0xb800, v141
	ds_read2_b64 v[248:251], v252 offset0:200 offset1:204
	s_waitcnt lgkmcnt(3)
; __device__ __forceinline__ void attn_unit(LAS unsigned char* lds, bf16_t* proj, const float* biasG, const float* sink, int s, int qb, int kh, int hp, bf16_t* dummy = nullptr) {
;     ...
;             if (st < wq || st > wq + 8) continue;
;             f32x4 sa[2][2];
; #pragma unroll
;             for (int kt = 0; kt < 2; ++kt) { sa[kt][0] = (f32x4){0.f, 0.f, 0.f, 0.f}; sa[kt][1] = (f32x4){0.f, 0.f, 0.f, 0.f}; }
; #pragma unroll
;             for (int ks = 0; ks < 4; ++ks)
; #pragma unroll
;                 for (int kt = 0; kt < 2; ++kt) {
;                     const bf16x8 kf = *(const LAS bf16x8*)(Ks + (si * 32 + kt * 16 + l16) * 272 + ks * 64 + kg * 16);
;                     sa[kt][0] = __builtin_amdgcn_mfma_f32_16x16x32_bf16(kf, qf[0][ks], sa[kt][0], 0, 0, 0);
;                     sa[kt][1] = __builtin_amdgcn_mfma_f32_16x16x32_bf16(kf, qf[1][ks], sa[kt][1], 0, 0, 0);
;                 }
;             bf16x8 pf[2];
; #pragma unroll
;             for (int qt = 0; qt < 2; ++qt) {
;                 const int qp = wq * 32 + qt * 16 + l16;
;                 float sv[8]; float mx = -1e30f;
; #pragma unroll
;                 for (int kt = 0; kt < 2; ++kt)
; #pragma unroll
;                     for (int r = 0; r < 4; ++r) {
;                         const int kp = (kbi - 1) * 128 + si * 32 + kt * 16 + kg * 4 + r;
;                         const int rel = kp - qp; const bool valid = (rel >= -128) && (rel <= 128);
;                         const int idx = min(max(rel + 128, 0), 256);
;                         const float v = valid ? (sa[kt][qt][r] * SC + bL[hl * 260 + idx]) : -1e30f;
;                         sv[kt * 4 + r] = v; mx = fmaxf(mx, v);
;                     }
;                 mx = fmaxf(mx, __shfl_xor(mx, 16)); mx = fmaxf(mx, __shfl_xor(mx, 32));
;     ...
;             for (int dt = 0; dt < 8; ++dt) {
;                 const LAS unsigned char* vr = Vt + (dt * 16 + l16) * 288 + (si * 32 + kg * 4) * 2;
;                 const u32x2 lo = *(const LAS u32x2*)(vr), hi = *(const LAS u32x2*)(vr + 32);
;                 u32x4 vw; vw.x = lo.x; vw.y = lo.y; vw.z = hi.x; vw.w = hi.y;
;                 const bf16x8 vf = __builtin_bit_cast(bf16x8, vw);
;                 o[dt][0] = __builtin_amdgcn_mfma_f32_16x16x32_bf16(vf, pf[0], o[dt][0], 0, 0, 0);
;                 o[dt][1] = __builtin_amdgcn_mfma_f32_16x16x32_bf16(vf, pf[1], o[dt][1], 0, 0, 0);
;             }
	v_mfma_f32_16x16x32_bf16 v[96:99], v[236:239], v[132:135], v[96:99]
	v_mov_b32_e32 v222, v3
	v_mfma_f32_16x16x32_bf16 v[68:71], v[236:239], v[136:139], v[68:71]
	v_add_u32_e32 v252, 0xd000, v141
	ds_read2_b64 v[236:239], v252 offset0:8 offset1:12
	s_waitcnt lgkmcnt(3)
	v_mfma_f32_16x16x32_bf16 v[104:107], v[240:243], v[132:135], v[104:107]
	v_mfma_f32_16x16x32_bf16 v[72:75], v[240:243], v[136:139], v[72:75]
	v_add_u32_e32 v252, 0xe000, v141
	ds_read2_b64 v[240:243], v252 offset0:72 offset1:76
	v_add_u32_e32 v141, 0xf000, v141
	s_waitcnt lgkmcnt(3)
	v_mfma_f32_16x16x32_bf16 v[108:111], v[244:247], v[132:135], v[108:111]
	v_mfma_f32_16x16x32_bf16 v[76:79], v[244:247], v[136:139], v[76:79]
	ds_read2_b64 v[244:247], v141 offset0:136 offset1:140
	s_waitcnt lgkmcnt(3)
	v_mfma_f32_16x16x32_bf16 v[112:115], v[248:251], v[132:135], v[112:115]
	v_mfma_f32_16x16x32_bf16 v[80:83], v[248:251], v[136:139], v[80:83]
	ds_read2_b64 v[248:251], v216 offset0:192 offset1:196
	s_waitcnt lgkmcnt(3)
	v_mfma_f32_16x16x32_bf16 v[116:119], v[236:239], v[132:135], v[116:119]
	v_mfma_f32_16x16x32_bf16 v[84:87], v[236:239], v[136:139], v[84:87]
	s_waitcnt lgkmcnt(2)
	v_mfma_f32_16x16x32_bf16 v[120:123], v[240:243], v[132:135], v[120:123]
	v_mfma_f32_16x16x32_bf16 v[88:91], v[240:243], v[136:139], v[88:91]
	s_waitcnt lgkmcnt(1)
	v_mfma_f32_16x16x32_bf16 v[124:127], v[244:247], v[132:135], v[124:127]
	v_mfma_f32_16x16x32_bf16 v[92:95], v[244:247], v[136:139], v[92:95]
	s_waitcnt lgkmcnt(0)
	v_mfma_f32_16x16x32_bf16 v[128:131], v[248:251], v[132:135], v[128:131]
	v_mfma_f32_16x16x32_bf16 v[100:103], v[248:251], v[136:139], v[100:103]
.LBB0_733:
	s_or_b64 exec, exec, s[74:75]
	s_add_i32 s4, s30, -1
	v_cmp_ge_u32_e32 vcc, s4, v192
	v_cmp_le_u32_e64 s[4:5], s4, v195
	s_and_b64 s[4:5], vcc, s[4:5]
	s_and_saveexec_b64 s[74:75], s[4:5]
	s_cbranch_execz .LBB0_767
	v_add_u32_e32 v251, 0x11700, v201
	v_add_u32_e32 v251, v251, v196
	ds_read_b32 v235, v251 offset:512
	ds_read_b32 v236, v251 offset:516
	ds_read_b32 v237, v251 offset:520
	ds_read_b32 v238, v251 offset:524
	ds_read_b32 v239, v251 offset:576
	ds_read_b32 v240, v251 offset:580
	ds_read_b32 v241, v251 offset:584
	ds_read_b32 v242, v251 offset:588
	ds_read_b32 v243, v251 offset:448
	ds_read_b32 v244, v251 offset:452
	ds_read_b32 v245, v251 offset:456
	ds_read_b32 v246, v251 offset:460
	ds_read_b32 v247, v251 offset:512
	ds_read_b32 v248, v251 offset:516
	ds_read_b32 v249, v251 offset:520
	ds_read_b32 v250, v251 offset:524
	ds_read_b128 v[140:143], v211
	ds_read_b128 v[132:135], v213 offset:21760
	ds_read_b128 v[226:229], v211 offset:64
	ds_read_b128 v[230:233], v213 offset:21824
	v_subrev_u32_e32 v1, 51, v199
	v_cmp_gt_u32_e32 vcc, s53, v1
	v_add3_u32 v2, v201, v196, s14
	s_waitcnt lgkmcnt(3)
	v_mfma_f32_16x16x32_bf16 v[144:147], v[140:143], v[4:7], 0
	v_mfma_f32_16x16x32_bf16 v[140:143], v[140:143], v[20:23], 0
	s_waitcnt lgkmcnt(2)
	v_mfma_f32_16x16x32_bf16 v[136:139], v[132:135], v[20:23], 0
	v_mfma_f32_16x16x32_bf16 v[132:135], v[132:135], v[4:7], 0
	s_waitcnt lgkmcnt(1)
	v_mfma_f32_16x16x32_bf16 v[144:147], v[226:229], v[8:11], v[144:147]
	v_mfma_f32_16x16x32_bf16 v[140:143], v[226:229], v[24:27], v[140:143]
	ds_read_b128 v[226:229], v211 offset:128
	s_waitcnt lgkmcnt(1)
	v_mfma_f32_16x16x32_bf16 v[132:135], v[230:233], v[8:11], v[132:135]
	v_mfma_f32_16x16x32_bf16 v[136:139], v[230:233], v[24:27], v[136:139]
	ds_read_b128 v[230:233], v213 offset:21888
	s_waitcnt lgkmcnt(1)
	v_mfma_f32_16x16x32_bf16 v[144:147], v[226:229], v[12:15], v[144:147]
	v_mfma_f32_16x16x32_bf16 v[140:143], v[226:229], v[28:31], v[140:143]
	ds_read_b128 v[226:229], v211 offset:192
	s_waitcnt lgkmcnt(1)
	v_mfma_f32_16x16x32_bf16 v[132:135], v[230:233], v[12:15], v[132:135]
	v_mfma_f32_16x16x32_bf16 v[136:139], v[230:233], v[28:31], v[136:139]
	ds_read_b128 v[230:233], v213 offset:21952
	s_waitcnt lgkmcnt(1)
	v_mfma_f32_16x16x32_bf16 v[144:147], v[226:229], v[16:19], v[144:147]
	v_mfma_f32_16x16x32_bf16 v[140:143], v[226:229], v[32:35], v[140:143]
	s_waitcnt lgkmcnt(0)
	v_mfma_f32_16x16x32_bf16 v[132:135], v[230:233], v[16:19], v[132:135]
	v_mfma_f32_16x16x32_bf16 v[136:139], v[230:233], v[32:35], v[136:139]
	s_nop 2
	v_mov_b32_e32 v251, 0xf149f2ca
	s_waitcnt lgkmcnt(0)
	v_fmac_f32_e32 v235, 0x3e0293ee, v144
	v_cndmask_b32_e32 v229, v251, v235, vcc
	v_subrev_u32_e32 v1, 50, v199
	v_cmp_gt_u32_e64 s[4:5], s53, v1
	v_add3_u32 v225, v201, v196, s54
	v_fmac_f32_e32 v236, 0x3e0293ee, v145
	v_cndmask_b32_e64 v228, v251, v236, s[4:5]
	v_subrev_u32_e32 v1, 49, v199
	v_cmp_gt_u32_e64 s[6:7], s53, v1
	v_add3_u32 v226, v201, v196, s58
	v_fmac_f32_e32 v237, 0x3e0293ee, v146
	v_cndmask_b32_e64 v230, v251, v237, s[6:7]
	v_subrev_u32_e32 v1, 48, v199
	v_cmp_gt_u32_e64 s[8:9], s53, v1
	v_add3_u32 v227, v201, v196, s97
	v_fmac_f32_e32 v238, 0x3e0293ee, v147
	v_cndmask_b32_e64 v145, v251, v238, s[8:9]
	v_subrev_u32_e32 v1, 35, v199
	v_cmp_gt_u32_e64 s[10:11], s53, v1
	v_fmac_f32_e32 v239, 0x3e0293ee, v132
	s_nop 0
	v_cndmask_b32_e64 v231, v251, v239, s[10:11]
	v_subrev_u32_e32 v1, 34, v199
	v_cmp_gt_u32_e64 s[10:11], s53, v1
	v_fmac_f32_e32 v240, 0x3e0293ee, v133
	s_nop 0
	v_cndmask_b32_e64 v232, v251, v240, s[10:11]
	v_subrev_u32_e32 v1, 33, v199
	v_cmp_gt_u32_e64 s[10:11], s53, v1
	v_fmac_f32_e32 v241, 0x3e0293ee, v134
	s_nop 0
	v_cndmask_b32_e64 v133, v251, v241, s[10:11]
	v_subrev_u32_e32 v1, 32, v199
	v_cmp_gt_u32_e64 s[10:11], s53, v1
	v_fmac_f32_e32 v242, 0x3e0293ee, v135
	s_nop 0
	v_cndmask_b32_e64 v132, v251, v242, s[10:11]
	v_mov_b32_e32 v144, 0xf149f2ca
	v_max3_f32 v1, v229, v144, v228
	v_max3_f32 v1, v1, v230, v145
	v_max3_f32 v1, v1, v231, v232
	v_max3_f32 v1, v1, v133, v132
	v_mov_b32_e32 v253, v1
	v_mov_b32_e32 v135, v1
	s_nop 1
	v_permlane16_swap_b32_e32 v253, v135
	v_max_f32_e32 v135, v135, v253
	s_waitcnt lgkmcnt(0)
; __device__ __forceinline__ void attn_unit(LAS unsigned char* lds, bf16_t* proj, const float* biasG, const float* sink, int s, int qb, int kh, int hp, bf16_t* dummy = nullptr) {
;     ...
;                 float sv[8]; float mx = -1e30f;
; #pragma unroll
;                 for (int kt = 0; kt < 2; ++kt)
; #pragma unroll
;                     for (int r = 0; r < 4; ++r) {
;                         const int kp = (kbi - 1) * 128 + si * 32 + kt * 16 + kg * 4 + r;
;                         const int rel = kp - qp; const bool valid = (rel >= -128) && (rel <= 128);
;                         const int idx = min(max(rel + 128, 0), 256);
;                         const float v = valid ? (sa[kt][qt][r] * SC + bL[hl * 260 + idx]) : -1e30f;
;                         sv[kt * 4 + r] = v; mx = fmaxf(mx, v);
;                     }
;                 mx = fmaxf(mx, __shfl_xor(mx, 16)); mx = fmaxf(mx, __shfl_xor(mx, 32));
;                 const float mnew = fmaxf(m2[qt], mx), alpha = __builtin_amdgcn_exp2f(m2[qt] - mnew); m2[qt] = mnew;
;                 float ps = 0.f; float pv[8];
; #pragma unroll
;                 for (int i = 0; i < 8; ++i) { pv[i] = __builtin_amdgcn_exp2f(sv[i] - mnew); ps += pv[i]; }
;                 lsum[qt] = lsum[qt] * alpha + ps;
	v_max_f32_e32 v134, v135, v135
	v_max_f32_e32 v1, v1, v134
	v_mov_b32_e32 v253, v1
	v_mov_b32_e32 v134, v1
	s_nop 1
	v_permlane32_swap_b32_e32 v253, v134
	v_max_f32_e32 v134, v134, v253
	s_waitcnt lgkmcnt(0)
	v_max3_f32 v1, v224, v1, v134
	v_sub_f32_e32 v134, v229, v1
	v_exp_f32_e32 v147, v134
	v_sub_f32_e32 v134, v228, v1
	v_exp_f32_e32 v228, v134
	v_sub_f32_e32 v134, v230, v1
	v_exp_f32_e32 v229, v134
	v_sub_f32_e32 v134, v145, v1
	v_exp_f32_e32 v230, v134
	v_sub_f32_e32 v134, v231, v1
	v_exp_f32_e32 v231, v134
	v_sub_f32_e32 v134, v232, v1
	v_sub_f32_e32 v133, v133, v1
	v_sub_f32_e32 v132, v132, v1
	v_exp_f32_e32 v232, v134
	v_exp_f32_e32 v233, v133
	v_exp_f32_e32 v234, v132
	v_add_u32_e32 v145, 0xffffffbd, v199
	v_cmp_gt_u32_e64 s[10:11], s53, v145
	v_cvt_pk_bf16_f32 v132, v147, v228
	v_cvt_pk_bf16_f32 v133, v229, v230
	v_cvt_pk_bf16_f32 v134, v231, v232
	v_cvt_pk_bf16_f32 v135, v233, v234
	v_fmac_f32_e32 v243, 0x3e0293ee, v140
	v_cndmask_b32_e64 v145, v251, v243, s[10:11]
	v_add_u32_e32 v140, 0xffffffbe, v199
	v_cmp_gt_u32_e64 s[10:11], s53, v140
	v_fmac_f32_e32 v244, 0x3e0293ee, v141
	s_nop 0
	v_cndmask_b32_e64 v144, v144, v244, s[10:11]
	v_add_u32_e32 v140, 0xffffffbf, v199
	v_cmp_gt_u32_e64 s[10:11], s53, v140
	v_fmac_f32_e32 v245, 0x3e0293ee, v142
	s_nop 0
	v_cndmask_b32_e64 v141, v251, v245, s[10:11]
	v_subrev_u32_e32 v142, 64, v199
	v_cmp_gt_u32_e64 s[10:11], s53, v142
	v_fmac_f32_e32 v246, 0x3e0293ee, v143
	s_nop 0
	v_cndmask_b32_e64 v140, v251, v246, s[10:11]
	v_fmac_f32_e32 v247, 0x3e0293ee, v136
	v_cndmask_b32_e32 v143, v251, v247, vcc
	v_fmac_f32_e32 v248, 0x3e0293ee, v137
	v_cndmask_b32_e64 v142, v251, v248, s[4:5]
	v_fmac_f32_e32 v249, 0x3e0293ee, v138
	v_cndmask_b32_e64 v137, v251, v249, s[6:7]
	v_fmac_f32_e32 v250, 0x3e0293ee, v139
	v_cndmask_b32_e64 v136, v251, v250, s[8:9]
	v_max3_f32 v2, v145, s89, v144
	v_max3_f32 v2, v2, v141, v140
	v_max3_f32 v139, v2, v143, v142
	v_add_f32_e32 v2, 0, v147
	v_add_f32_e32 v2, v228, v2
	v_add_f32_e32 v2, v229, v2
	v_sub_f32_e32 v138, v224, v1
	v_add_f32_e32 v2, v230, v2
	v_add_f32_e32 v2, v231, v2
	v_exp_f32_e32 v138, v138
	v_add_f32_e32 v2, v232, v2
	v_add_f32_e32 v2, v233, v2
	v_add_f32_e32 v2, v234, v2
	v_fmac_f32_e32 v2, v223, v138
	v_pk_mul_f32 v[98:99], v[98:99], v[138:139] op_sel_hi:[1,0]
	v_pk_mul_f32 v[96:97], v[96:97], v[138:139] op_sel_hi:[1,0]
	v_pk_mul_f32 v[106:107], v[106:107], v[138:139] op_sel_hi:[1,0]
	v_pk_mul_f32 v[104:105], v[104:105], v[138:139] op_sel_hi:[1,0]
	v_pk_mul_f32 v[110:111], v[110:111], v[138:139] op_sel_hi:[1,0]
	v_pk_mul_f32 v[108:109], v[108:109], v[138:139] op_sel_hi:[1,0]
	v_pk_mul_f32 v[114:115], v[114:115], v[138:139] op_sel_hi:[1,0]
	v_pk_mul_f32 v[112:113], v[112:113], v[138:139] op_sel_hi:[1,0]
	v_pk_mul_f32 v[118:119], v[118:119], v[138:139] op_sel_hi:[1,0]
	v_pk_mul_f32 v[116:117], v[116:117], v[138:139] op_sel_hi:[1,0]
	v_pk_mul_f32 v[122:123], v[122:123], v[138:139] op_sel_hi:[1,0]
	v_pk_mul_f32 v[120:121], v[120:121], v[138:139] op_sel_hi:[1,0]
	v_pk_mul_f32 v[126:127], v[126:127], v[138:139] op_sel_hi:[1,0]
	v_pk_mul_f32 v[124:125], v[124:125], v[138:139] op_sel_hi:[1,0]
	v_pk_mul_f32 v[130:131], v[130:131], v[138:139] op_sel_hi:[1,0]
	v_pk_mul_f32 v[128:129], v[128:129], v[138:139] op_sel_hi:[1,0]
	v_max3_f32 v138, v139, v137, v136
	v_mov_b32_e32 v253, v138
	v_mov_b32_e32 v139, v138
	s_nop 1
	v_permlane16_swap_b32_e32 v253, v139
	v_max_f32_e32 v139, v139, v253
	v_mov_b32_e32 v223, v2
	v_mov_b32_e32 v224, v1
	s_waitcnt lgkmcnt(0)
	v_max_f32_e32 v139, v139, v139
	v_max_f32_e32 v138, v138, v139
	v_mov_b32_e32 v253, v138
	v_mov_b32_e32 v3, v138
	s_nop 1
	v_permlane32_swap_b32_e32 v253, v3
	v_max_f32_e32 v3, v3, v253
	s_waitcnt lgkmcnt(0)
; #define LAS __attribute__((address_space(3)))
; __device__ __forceinline__ unsigned cvt_pk_bf16(float lo, float hi) { unsigned r; asm volatile("v_cvt_pk_bf16_f32 %0, %1, %2" : "=v"(r) : "v"(lo), "v"(hi)); return r; }
; __device__ __forceinline__ void attn_unit(LAS unsigned char* lds, bf16_t* proj, const float* biasG, const float* sink, int s, int qb, int kh, int hp, bf16_t* dummy = nullptr) {
;     ...
;                 const float mnew = fmaxf(m2[qt], mx), alpha = __builtin_amdgcn_exp2f(m2[qt] - mnew); m2[qt] = mnew;
;                 float ps = 0.f; float pv[8];
; #pragma unroll
;                 for (int i = 0; i < 8; ++i) { pv[i] = __builtin_amdgcn_exp2f(sv[i] - mnew); ps += pv[i]; }
;                 lsum[qt] = lsum[qt] * alpha + ps;
; #pragma unroll
;                 for (int dt = 0; dt < 8; ++dt) o[dt][qt] = o[dt][qt] * alpha;
;                 u32x4 pw; pw.x = cvt_pk_bf16(pv[0], pv[1]); pw.y = cvt_pk_bf16(pv[2], pv[3]); pw.z = cvt_pk_bf16(pv[4], pv[5]); pw.w = cvt_pk_bf16(pv[6], pv[7]);
;                 pf[qt] = __builtin_bit_cast(bf16x8, pw);
;             }
; #pragma unroll
;             for (int dt = 0; dt < 8; ++dt) {
;                 const LAS unsigned char* vr = Vt + (dt * 16 + l16) * 288 + (si * 32 + kg * 4) * 2;
;                 const u32x2 lo = *(const LAS u32x2*)(vr), hi = *(const LAS u32x2*)(vr + 32);
;                 u32x4 vw; vw.x = lo.x; vw.y = lo.y; vw.z = hi.x; vw.w = hi.y;
;                 const bf16x8 vf = __builtin_bit_cast(bf16x8, vw);
;                 o[dt][0] = __builtin_amdgcn_mfma_f32_16x16x32_bf16(vf, pf[0], o[dt][0], 0, 0, 0);
;                 o[dt][1] = __builtin_amdgcn_mfma_f32_16x16x32_bf16(vf, pf[1], o[dt][1], 0, 0, 0);
;             }
	v_max3_f32 v3, v222, v138, v3
	v_sub_f32_e32 v139, v145, v3
	v_exp_f32_e32 v139, v139
	v_sub_f32_e32 v144, v144, v3
	v_exp_f32_e32 v144, v144
	v_sub_f32_e32 v141, v141, v3
	v_exp_f32_e32 v141, v141
	v_sub_f32_e32 v140, v140, v3
	v_exp_f32_e32 v146, v140
	v_add_f32_e32 v145, 0, v139
	v_sub_f32_e32 v143, v143, v3
	v_add_f32_e32 v145, v144, v145
	v_exp_f32_e32 v143, v143
	v_sub_f32_e32 v142, v142, v3
	v_add_f32_e32 v145, v141, v145
	v_exp_f32_e32 v142, v142
	v_sub_f32_e32 v137, v137, v3
	v_add_f32_e32 v140, v146, v145
	v_exp_f32_e32 v145, v137
	v_sub_f32_e32 v136, v136, v3
	v_sub_f32_e32 v138, v222, v3
	v_exp_f32_e32 v147, v136
	v_add_f32_e32 v140, v143, v140
	v_exp_f32_e32 v136, v138
	v_add_f32_e32 v140, v142, v140
	v_add_f32_e32 v137, v145, v140
	v_add_f32_e32 v140, v147, v137
	v_fmac_f32_e32 v140, v221, v136
	v_pk_mul_f32 v[70:71], v[70:71], v[136:137] op_sel_hi:[1,0]
	v_pk_mul_f32 v[68:69], v[68:69], v[136:137] op_sel_hi:[1,0]
	v_pk_mul_f32 v[74:75], v[74:75], v[136:137] op_sel_hi:[1,0]
	v_pk_mul_f32 v[72:73], v[72:73], v[136:137] op_sel_hi:[1,0]
	v_pk_mul_f32 v[78:79], v[78:79], v[136:137] op_sel_hi:[1,0]
	v_pk_mul_f32 v[76:77], v[76:77], v[136:137] op_sel_hi:[1,0]
	v_pk_mul_f32 v[82:83], v[82:83], v[136:137] op_sel_hi:[1,0]
	v_pk_mul_f32 v[80:81], v[80:81], v[136:137] op_sel_hi:[1,0]
	v_pk_mul_f32 v[86:87], v[86:87], v[136:137] op_sel_hi:[1,0]
	v_pk_mul_f32 v[84:85], v[84:85], v[136:137] op_sel_hi:[1,0]
	v_pk_mul_f32 v[90:91], v[90:91], v[136:137] op_sel_hi:[1,0]
	v_pk_mul_f32 v[88:89], v[88:89], v[136:137] op_sel_hi:[1,0]
	v_pk_mul_f32 v[94:95], v[94:95], v[136:137] op_sel_hi:[1,0]
	v_pk_mul_f32 v[92:93], v[92:93], v[136:137] op_sel_hi:[1,0]
	v_pk_mul_f32 v[102:103], v[102:103], v[136:137] op_sel_hi:[1,0]
	v_pk_mul_f32 v[100:101], v[100:101], v[136:137] op_sel_hi:[1,0]
	v_cvt_pk_bf16_f32 v136, v139, v144
	v_cvt_pk_bf16_f32 v137, v141, v146
	v_add_u32_e32 v141, v197, v198
	v_cvt_pk_bf16_f32 v138, v143, v142
	v_add_u32_e32 v142, 0x8800, v141
	v_cvt_pk_bf16_f32 v139, v145, v147
	ds_read2_b64 v[236:239], v142 offset0:16 offset1:20
	v_mov_b32_e32 v221, v140
	v_add_u32_e32 v252, 0x9800, v141
	ds_read2_b64 v[240:243], v252 offset0:80 offset1:84
	v_add_u32_e32 v252, 0xa800, v141
	ds_read2_b64 v[244:247], v252 offset0:144 offset1:148
	v_add_u32_e32 v252, 0xb800, v141
	ds_read2_b64 v[248:251], v252 offset0:208 offset1:212
	s_waitcnt lgkmcnt(3)
	v_mfma_f32_16x16x32_bf16 v[96:99], v[236:239], v[132:135], v[96:99]
	v_mov_b32_e32 v222, v3
	v_mfma_f32_16x16x32_bf16 v[68:71], v[236:239], v[136:139], v[68:71]
	ds_read2_b64 v[236:239], v217 offset0:16 offset1:20
	s_waitcnt lgkmcnt(3)
	v_mfma_f32_16x16x32_bf16 v[104:107], v[240:243], v[132:135], v[104:107]
	v_mfma_f32_16x16x32_bf16 v[72:75], v[240:243], v[136:139], v[72:75]
	v_add_u32_e32 v252, 0xe000, v141
	ds_read2_b64 v[240:243], v252 offset0:80 offset1:84
	v_add_u32_e32 v141, 0xf000, v141
	s_waitcnt lgkmcnt(3)
	v_mfma_f32_16x16x32_bf16 v[108:111], v[244:247], v[132:135], v[108:111]
	v_mfma_f32_16x16x32_bf16 v[76:79], v[244:247], v[136:139], v[76:79]
	ds_read2_b64 v[244:247], v141 offset0:144 offset1:148
	s_waitcnt lgkmcnt(3)
	v_mfma_f32_16x16x32_bf16 v[112:115], v[248:251], v[132:135], v[112:115]
	v_mfma_f32_16x16x32_bf16 v[80:83], v[248:251], v[136:139], v[80:83]
	ds_read2_b64 v[248:251], v218 offset0:192 offset1:196
	s_waitcnt lgkmcnt(3)
	v_mfma_f32_16x16x32_bf16 v[116:119], v[236:239], v[132:135], v[116:119]
	v_mfma_f32_16x16x32_bf16 v[84:87], v[236:239], v[136:139], v[84:87]
	s_waitcnt lgkmcnt(2)
	v_mfma_f32_16x16x32_bf16 v[120:123], v[240:243], v[132:135], v[120:123]
	v_mfma_f32_16x16x32_bf16 v[88:91], v[240:243], v[136:139], v[88:91]
	s_waitcnt lgkmcnt(1)
	v_mfma_f32_16x16x32_bf16 v[124:127], v[244:247], v[132:135], v[124:127]
	v_mfma_f32_16x16x32_bf16 v[92:95], v[244:247], v[136:139], v[92:95]
	s_waitcnt lgkmcnt(0)
	v_mfma_f32_16x16x32_bf16 v[128:131], v[248:251], v[132:135], v[128:131]
	v_mfma_f32_16x16x32_bf16 v[100:103], v[248:251], v[136:139], v[100:103]
